# split barrier at the layer boundary: next layer's weight conversion starts without waiting for FFN2-down; completes the barrier before converting W_D2
# baseline (speedup 1.0000x reference)
.LBB0_1814:
	s_mov_b32 s101, -1
	s_getreg_b32 s14, hwreg(HW_REG_XCC_ID, 0, 4)
	s_waitcnt vmcnt(0)
	s_waitcnt lgkmcnt(0)
	s_barrier
	s_and_saveexec_b64 s[0:1], s[46:47]
	s_cbranch_execz .LBB0_1866
	s_add_i32 s15, 0, 0x20160
	v_mov_b32_e32 v0, s15
	s_waitcnt vmcnt(0) expcnt(0) lgkmcnt(0)
	ds_read_b32 v2, v0
	s_add_i32 s15, 0, 0x20164
	v_mov_b32_e32 v0, s15
	ds_read_b32 v0, v0
	s_and_b32 s51, s14, 15
	s_waitcnt lgkmcnt(1)
	v_cmp_ne_u32_e32 vcc, 0, v2
	s_cbranch_vccnz .LBB0_1830
	s_add_u32 s14, s66, 0x1200
	s_addc_u32 s15, s67, 0
	s_add_u32 s16, s66, 0x1400
	s_addc_u32 s17, s67, 0
	s_add_u32 s18, s66, 0x1500
	s_addc_u32 s19, s67, 0
	s_add_u32 s20, s66, 0x1600
	s_addc_u32 s21, s67, 0
	s_add_u32 s22, s66, 0x1700
	s_addc_u32 s23, s67, 0
	s_add_u32 s24, s66, 0x1800
	s_addc_u32 s25, s67, 0
	s_add_u32 s26, s66, 0x1900
	s_addc_u32 s27, s67, 0
	s_add_u32 s28, s66, 0x1a00
	s_addc_u32 s29, s67, 0
	s_add_u32 s30, s66, 0x1b00
	s_addc_u32 s31, s67, 0
	s_add_u32 s34, s66, 0x1c00
	s_addc_u32 s35, s67, 0
	s_add_u32 s36, s66, 0x1d00
	s_addc_u32 s37, s67, 0
	s_add_u32 s38, s66, 0x1e00
	s_addc_u32 s39, s67, 0
	s_add_u32 s40, s66, 0x1f00
	s_addc_u32 s41, s67, 0
	s_add_u32 s42, s66, 0x2000
	s_addc_u32 s43, s67, 0
	s_add_u32 s44, s66, 0x2100
	s_addc_u32 s45, s67, 0
	s_add_u32 s56, s66, 0x2200
	s_addc_u32 s57, s67, 0
	s_mul_i32 s72, s65, s74
	s_add_u32 s58, s66, 0x2300
	s_mul_i32 s72, s72, s64
	s_addc_u32 s59, s67, 0
	s_mov_b32 s73, 1
	v_mov_b32_e32 v16, 0
	s_branch .LBB0_1818

.LBB0_1832:
	s_or_b64 exec, exec, s[18:19]
	v_cvt_f32_u32_e32 v4, v2
	s_waitcnt vmcnt(0)
	v_readfirstlane_b32 s16, v3
	v_sub_u32_e32 v3, 0, v2
	v_rcp_iflag_f32_e32 v4, v4
	v_add_u32_e32 v5, s16, v1
	v_mul_f32_e32 v4, 0x4f7ffffe, v4
	v_cvt_u32_f32_e32 v4, v4
	v_mul_lo_u32 v1, v3, v4
	v_mul_hi_u32 v1, v4, v1
	v_add_u32_e32 v1, v4, v1
	v_mul_hi_u32 v1, v5, v1
	v_mul_lo_u32 v3, v1, v2
	v_sub_u32_e32 v3, v5, v3
	v_add_u32_e32 v4, 1, v1
	v_cmp_ge_u32_e32 vcc, v3, v2
	s_nop 1
	v_cndmask_b32_e32 v1, v1, v4, vcc
	v_sub_u32_e32 v4, v3, v2
	v_cndmask_b32_e32 v3, v3, v4, vcc
	v_add_u32_e32 v4, 1, v1
	v_cmp_ge_u32_e32 vcc, v3, v2
	v_add_u32_e32 v3, 1, v5
	s_nop 0
	v_cndmask_b32_e32 v1, v1, v4, vcc
	v_mul_lo_u32 v4, v2, v1
	v_add_u32_e32 v2, v4, v2
	v_cmp_ne_u32_e32 vcc, v3, v2
	s_and_saveexec_b64 s[16:17], vcc
	s_xor_b64 s[16:17], exec, s[16:17]
	s_cbranch_execz .LBB0_1846
	s_cmp_lt_u32 s2, 0
	s_cbranch_scc1 .Lsb_wait_q0
	s_cmp_lg_u32 s64, 0x100
	s_cbranch_scc1 .Lsb_wait_q0
	v_readfirstlane_b32 s101, v1
	s_branch .LBB0_1846
.Lsb_wait_q0:
	s_waitcnt lgkmcnt(0)
	buffer_inv sc1
	v_mov_b32_e32 v0, 0x2000
	global_load_dword v0, v0, s[14:15] offset:1024 sc1
	s_add_u32 s22, s14, 0x2400
	s_addc_u32 s23, s15, 0
	s_waitcnt vmcnt(0)
	v_cmp_eq_u32_e32 vcc, v0, v1
	s_and_saveexec_b64 s[18:19], vcc
	s_cbranch_execz .LBB0_1845
	s_add_u32 s20, s66, 0x1200
	s_addc_u32 s21, s67, 0
	s_mov_b32 s36, 1
	s_mov_b64 s[24:25], 0
	v_mov_b32_e32 v0, 0
	s_branch .LBB0_1836

.LBB0_1875:
	v_readfirstlane_b32 s98, v194
	s_cmp_lg_u32 s98, 0
	s_cbranch_scc1 .Lsb_cj_q0
	s_cmp_eq_u32 s101, -1
	s_cbranch_scc1 .Lsb_cj_q0
	s_getreg_b32 s98, hwreg(HW_REG_XCC_ID, 0, 4)
	s_lshl_b32 s98, s98, 8
	s_add_i32 s98, s98, 0x3400
	v_mov_b32_e32 v250, s98
	s_mov_b32 s99, 0

.Lsb_cj_q0:
	s_barrier
	s_andn2_b64 vcc, exec, s[14:15]
	s_cbranch_vccnz .LBB0_1878
	v_mov_b32_e32 v1, 0
	global_load_dwordx2 v[2:3], v1, s[20:21] offset:240
	s_waitcnt vmcnt(2)
	v_lshrrev_b32_e32 v6, 3, v32
	v_lshlrev_b32_e32 v0, 4, v48
	v_add_u32_e32 v10, s22, v0
	v_mul_u32_u24_e32 v11, 0x84, v6
	s_mov_b64 s[16:17], 0xb00000
	v_lshlrev_b32_e32 v8, 2, v48
	v_mul_u32_u24_e32 v9, 0x420, v48
	s_mov_b64 s[28:29], 0x1c80000
	s_movk_i32 s15, 0xb00
	v_mov_b32_e32 v7, s24
	v_lshl_add_u64 v[0:1], s[20:21], 0, v[0:1]
	v_lshlrev_b32_e32 v12, 2, v6
	v_add_u32_e32 v10, v10, v11
	s_lshl_b32 s0, s19, 5
	s_movk_i32 s1, 0x7fff
	s_mov_b32 s14, 0xffff0000
	v_mad_u32_u24 v7, v6, s15, v7
	v_lshl_or_b32 v8, s18, 5, v8
	v_lshl_add_u64 v[0:1], v[0:1], 0, s[28:29]
	v_add3_u32 v9, s22, v9, v12
	v_add_u32_e32 v11, 0x420, v10
	v_add_u32_e32 v12, 0x428, v10
	v_add_u32_e32 v13, 0x840, v10
	v_add_u32_e32 v14, 0x848, v10
	v_add_u32_e32 v15, 0xc60, v10
	v_add_u32_e32 v16, 0xc68, v10
	v_add_u32_e32 v17, 0x1080, v10
	v_add_u32_e32 v18, 0x1088, v10
	v_add_u32_e32 v19, 0x14a0, v10
	v_add_u32_e32 v20, 0x14a8, v10
	v_add_u32_e32 v21, 0x18c0, v10
	v_add_u32_e32 v22, 0x18c8, v10
	v_add_u32_e32 v23, 0x1ce0, v10
	v_add_u32_e32 v24, 0x1ce8, v10
	s_mov_b32 s15, s18
	s_waitcnt vmcnt(0)
	v_lshl_add_u64 v[2:3], v[2:3], 0, s[16:17]
